# MLA attention: running-max subtraction folded into the QK MFMA C operand (exp results in place in the score registers, row-sum moved into the QK phase), 34 VALU fewer per 64-key iteration, on top of v
# baseline (speedup 1.0000x reference)
.LBB0_426:
	s_lshl_b32 s7, s7, 2
	s_sub_i32 s9, 0, s8
	s_add_i32 s7, s7, 4
	s_waitcnt lgkmcnt(0)
	s_barrier
	s_cmp_eq_u32 s7, 0
	s_cbranch_scc1 .LBB0_447
	v_sub_f32_e32 v2, v2, v184
	v_sub_f32_e32 v3, v3, v184
	v_sub_f32_e32 v4, v4, v184
	v_sub_f32_e32 v5, v5, v184
	v_sub_f32_e32 v6, v6, v184
	v_sub_f32_e32 v7, v7, v184
	v_sub_f32_e32 v8, v8, v184
	v_sub_f32_e32 v9, v9, v184
	v_sub_f32_e32 v10, v10, v184
	v_sub_f32_e32 v11, v11, v184
	v_sub_f32_e32 v12, v12, v184
	v_sub_f32_e32 v13, v13, v184
	v_sub_f32_e32 v14, v14, v184
	v_sub_f32_e32 v15, v15, v184
	v_sub_f32_e32 v16, v16, v184
	v_sub_f32_e32 v17, v17, v184
	v_sub_f32_e32 v206, 0, v184
	v_sub_f32_e32 v207, 0, v184
	v_sub_f32_e32 v208, 0, v184
	v_sub_f32_e32 v209, 0, v184
	v_sub_f32_e32 v210, 0, v184
	v_sub_f32_e32 v211, 0, v184
	v_sub_f32_e32 v212, 0, v184
	v_sub_f32_e32 v213, 0, v184
	v_sub_f32_e32 v214, 0, v184
	v_sub_f32_e32 v215, 0, v184
	v_sub_f32_e32 v216, 0, v184
	v_sub_f32_e32 v217, 0, v184
	v_sub_f32_e32 v218, 0, v184
	v_sub_f32_e32 v219, 0, v184
	v_sub_f32_e32 v220, 0, v184
	v_sub_f32_e32 v221, 0, v184
	v_readlane_b32 s14, v251, 43
	v_readlane_b32 s15, v251, 44
	s_add_u32 s14, s14, s10
	s_addc_u32 s15, s15, s11
	v_mov_b32_e32 v175, v0
	v_lshl_add_u64 v[172:173], s[14:15], 0, v[174:175]
	v_readlane_b32 s14, v251, 53
	v_readlane_b32 s15, v251, 54
	s_mov_b32 s12, 1
	v_add_u32_e32 v185, v185, v182
	v_lshl_add_u64 v[174:175], s[14:15], 0, v[174:175]
	s_mov_b32 s8, 2
	s_lshl_b32 s9, s9, 2
	s_sub_i32 s14, 1, s6
	s_mov_b32 s24, 0
	s_movk_i32 s15, 0xffc0
	s_movk_i32 s76, 0xc0
	s_mov_b32 s18, 2
	s_mov_b32 s19, s12
	s_add_i32 s12, s15, 0x42
	s_cmp_ge_i32 s12, s7
	s_cbranch_scc1 .LBB0_429

.LBB0_436:
	v_add3_u32 v198, s20, v180, v182
	ds_read_b128 v[82:85], v198
	ds_read_b128 v[186:189], v198 offset:32
	s_mulk_i32 s24, 0x4800
	v_add_u32_e32 v223, s24, v185
	v_max_f32_e32 v204, v2, v3
	s_waitcnt lgkmcnt(1)
	v_mfma_f32_32x32x16_bf16 v[82:97], v[82:85], v[98:101], v[206:221]
	v_max3_f32 v204, v204, v4, v5
	v_max3_f32 v204, v204, v6, v7
	v_max3_f32 v204, v204, v8, v9
	v_max3_f32 v204, v204, v10, v11
	v_max3_f32 v204, v204, v12, v13
	v_max3_f32 v204, v204, v14, v15
	v_max3_f32 v204, v204, v16, v17
	s_waitcnt lgkmcnt(0)
	v_mfma_f32_32x32x16_bf16 v[82:97], v[186:189], v[102:105], v[82:97]
	ds_read_b128 v[186:189], v198 offset:64
	ds_read_b128 v[190:193], v198 offset:96
	v_exp_f32_e32 v2, v2
	v_exp_f32_e32 v3, v3
	v_exp_f32_e32 v4, v4
	v_exp_f32_e32 v5, v5
	v_exp_f32_e32 v6, v6
	v_exp_f32_e32 v7, v7
	s_waitcnt lgkmcnt(1)
	v_mfma_f32_32x32x16_bf16 v[82:97], v[186:189], v[106:109], v[82:97]
	v_exp_f32_e32 v8, v8
	v_exp_f32_e32 v9, v9
	v_add_f32_e32 v202, v3, v2
	v_add_f32_e32 v202, v4, v202
	v_add_f32_e32 v202, v5, v202
	v_add_f32_e32 v202, v6, v202
	v_add_f32_e32 v202, v7, v202
	s_waitcnt lgkmcnt(0)
	v_mfma_f32_32x32x16_bf16 v[82:97], v[190:193], v[110:113], v[82:97]
	ds_read_b128 v[186:189], v198 offset:128
	ds_read_b128 v[190:193], v198 offset:160
	v_exp_f32_e32 v10, v10
	v_exp_f32_e32 v11, v11
	v_exp_f32_e32 v12, v12
	v_exp_f32_e32 v13, v13
	v_add_f32_e32 v202, v8, v202
	v_add_f32_e32 v202, v9, v202
	s_waitcnt lgkmcnt(1)
	v_mfma_f32_32x32x16_bf16 v[82:97], v[186:189], v[114:117], v[82:97]
	ds_read_b128 v[186:189], v198 offset:192
	v_exp_f32_e32 v14, v14
	v_exp_f32_e32 v15, v15
	v_exp_f32_e32 v16, v16
	v_add_f32_e32 v202, v10, v202
	s_waitcnt lgkmcnt(1)
	v_mfma_f32_32x32x16_bf16 v[82:97], v[190:193], v[118:121], v[82:97]
	ds_read_b128 v[190:193], v198 offset:224
	v_add_f32_e32 v202, v11, v202
	v_add_f32_e32 v202, v12, v202
	v_add_f32_e32 v202, v13, v202
	v_add_f32_e32 v202, v14, v202
	v_add_f32_e32 v202, v15, v202
	v_add_f32_e32 v202, v16, v202
	s_waitcnt lgkmcnt(1)
	v_mfma_f32_32x32x16_bf16 v[82:97], v[186:189], v[122:125], v[82:97]
	ds_read_b128 v[186:189], v198 offset:256
	ds_bpermute_b32 v205, v178, v204
	v_exp_f32_e32 v17, v17
	s_waitcnt lgkmcnt(2)
	v_mfma_f32_32x32x16_bf16 v[82:97], v[190:193], v[126:129], v[82:97]
	ds_read_b128 v[190:193], v198 offset:288
	ds_read_b128 v[194:197], v198 offset:320
	ds_read_b128 v[198:201], v198 offset:352
	s_waitcnt lgkmcnt(4)
	v_mfma_f32_32x32x16_bf16 v[82:97], v[186:189], v[130:133], v[82:97]
	ds_read_b128 v[186:189], v223 offset:51264
	s_waitcnt lgkmcnt(3)
	v_mfma_f32_32x32x16_bf16 v[82:97], v[190:193], v[134:137], v[82:97]
	ds_read_b128 v[190:193], v223 offset:51296
	s_waitcnt lgkmcnt(3)
	v_mfma_f32_32x32x16_bf16 v[82:97], v[194:197], v[138:141], v[82:97]
	v_cvt_pk_bf16_f32 v194, v2, v3
	v_cvt_pk_bf16_f32 v195, v4, v5
	v_cvt_pk_bf16_f32 v196, v6, v7
	v_cvt_pk_bf16_f32 v197, v8, v9
	s_waitcnt lgkmcnt(1)
	s_nop 0
	v_mfma_f32_32x32x16_bf16 v[18:33], v[186:189], v[194:197], v[18:33]
	v_add_f32_e32 v202, v17, v202
	v_add_f32_e32 v183, v183, v202
	v_cvt_pk_bf16_f32 v186, v10, v11
	v_cvt_pk_bf16_f32 v187, v12, v13
	v_cvt_pk_bf16_f32 v188, v14, v15
	v_cvt_pk_bf16_f32 v189, v16, v17
	s_waitcnt lgkmcnt(0)
	v_max_f32_e32 v222, v204, v205
	v_mfma_f32_32x32x16_bf16 v[18:33], v[190:193], v[186:189], v[18:33]
	ds_read_b128 v[190:193], v223 offset:55872
	ds_read_b128 v[202:205], v223 offset:55904
	ds_read_b128 v[2:5], v223 offset:60512
	ds_read_b128 v[6:9], v223 offset:65088
	s_waitcnt lgkmcnt(3)
	v_mfma_f32_32x32x16_bf16 v[34:49], v[190:193], v[194:197], v[34:49]
	ds_read_b128 v[190:193], v223 offset:60480
	s_waitcnt lgkmcnt(0)
	v_mfma_f32_32x32x16_bf16 v[50:65], v[190:193], v[194:197], v[50:65]
	v_mfma_f32_32x32x16_bf16 v[50:65], v[2:5], v[186:189], v[50:65]
	ds_read_b128 v[2:5], v223 offset:65120
	v_mfma_f32_32x32x16_bf16 v[66:81], v[6:9], v[194:197], v[66:81]
	s_waitcnt lgkmcnt(0)
	v_mfma_f32_32x32x16_bf16 v[66:81], v[2:5], v[186:189], v[66:81]
	v_mfma_f32_32x32x16_bf16 v[34:49], v[202:205], v[186:189], v[34:49]
	v_cmp_lt_f32_e32 vcc, s2, v222
	v_mfma_f32_32x32x16_bf16 v[2:17], v[198:201], v[142:145], v[82:97]
	s_cbranch_vccz .LBB0_438
	v_max_f32_e32 v202, v222, v222
	v_max_f32_e32 v203, 0, v202
	v_exp_f32_e64 v202, -v203
	v_add_f32_e32 v184, v184, v203
	v_mul_f32_e32 v183, v183, v202
	v_pk_mul_f32 v[32:33], v[202:203], v[32:33] op_sel_hi:[0,1]
	v_pk_mul_f32 v[30:31], v[202:203], v[30:31] op_sel_hi:[0,1]
	v_pk_mul_f32 v[28:29], v[202:203], v[28:29] op_sel_hi:[0,1]
	v_pk_mul_f32 v[26:27], v[202:203], v[26:27] op_sel_hi:[0,1]
	v_pk_mul_f32 v[24:25], v[202:203], v[24:25] op_sel_hi:[0,1]
	v_pk_mul_f32 v[22:23], v[202:203], v[22:23] op_sel_hi:[0,1]
	v_pk_mul_f32 v[20:21], v[202:203], v[20:21] op_sel_hi:[0,1]
	v_pk_mul_f32 v[18:19], v[202:203], v[18:19] op_sel_hi:[0,1]
	v_pk_mul_f32 v[48:49], v[202:203], v[48:49] op_sel_hi:[0,1]
	v_pk_mul_f32 v[46:47], v[202:203], v[46:47] op_sel_hi:[0,1]
	v_pk_mul_f32 v[44:45], v[202:203], v[44:45] op_sel_hi:[0,1]
	v_pk_mul_f32 v[42:43], v[202:203], v[42:43] op_sel_hi:[0,1]
	v_pk_mul_f32 v[40:41], v[202:203], v[40:41] op_sel_hi:[0,1]
	v_pk_mul_f32 v[38:39], v[202:203], v[38:39] op_sel_hi:[0,1]
	v_pk_mul_f32 v[36:37], v[202:203], v[36:37] op_sel_hi:[0,1]
	v_pk_mul_f32 v[34:35], v[202:203], v[34:35] op_sel_hi:[0,1]
	v_pk_mul_f32 v[64:65], v[202:203], v[64:65] op_sel_hi:[0,1]
	v_pk_mul_f32 v[62:63], v[202:203], v[62:63] op_sel_hi:[0,1]
	v_pk_mul_f32 v[60:61], v[202:203], v[60:61] op_sel_hi:[0,1]
	v_pk_mul_f32 v[58:59], v[202:203], v[58:59] op_sel_hi:[0,1]
	v_pk_mul_f32 v[56:57], v[202:203], v[56:57] op_sel_hi:[0,1]
	v_pk_mul_f32 v[54:55], v[202:203], v[54:55] op_sel_hi:[0,1]
	v_pk_mul_f32 v[52:53], v[202:203], v[52:53] op_sel_hi:[0,1]
	v_pk_mul_f32 v[50:51], v[202:203], v[50:51] op_sel_hi:[0,1]
	v_pk_mul_f32 v[80:81], v[202:203], v[80:81] op_sel_hi:[0,1]
	v_pk_mul_f32 v[78:79], v[202:203], v[78:79] op_sel_hi:[0,1]
	v_pk_mul_f32 v[76:77], v[202:203], v[76:77] op_sel_hi:[0,1]
	v_pk_mul_f32 v[74:75], v[202:203], v[74:75] op_sel_hi:[0,1]
	v_pk_mul_f32 v[72:73], v[202:203], v[72:73] op_sel_hi:[0,1]
	v_pk_mul_f32 v[70:71], v[202:203], v[70:71] op_sel_hi:[0,1]
	v_pk_mul_f32 v[68:69], v[202:203], v[68:69] op_sel_hi:[0,1]
	v_pk_mul_f32 v[66:67], v[202:203], v[66:67] op_sel_hi:[0,1]
	v_sub_f32_e32 v2, v2, v203
	v_sub_f32_e32 v3, v3, v203
	v_sub_f32_e32 v4, v4, v203
	v_sub_f32_e32 v5, v5, v203
	v_sub_f32_e32 v6, v6, v203
	v_sub_f32_e32 v7, v7, v203
	v_sub_f32_e32 v8, v8, v203
	v_sub_f32_e32 v9, v9, v203
	v_sub_f32_e32 v10, v10, v203
	v_sub_f32_e32 v11, v11, v203
	v_sub_f32_e32 v12, v12, v203
	v_sub_f32_e32 v13, v13, v203
	v_sub_f32_e32 v14, v14, v203
	v_sub_f32_e32 v15, v15, v203
	v_sub_f32_e32 v16, v16, v203
	v_sub_f32_e32 v17, v17, v203
	v_sub_f32_e32 v206, v206, v203
	v_sub_f32_e32 v207, v207, v203
	v_sub_f32_e32 v208, v208, v203
	v_sub_f32_e32 v209, v209, v203
	v_sub_f32_e32 v210, v210, v203
	v_sub_f32_e32 v211, v211, v203
	v_sub_f32_e32 v212, v212, v203
	v_sub_f32_e32 v213, v213, v203
	v_sub_f32_e32 v214, v214, v203
	v_sub_f32_e32 v215, v215, v203
	v_sub_f32_e32 v216, v216, v203
	v_sub_f32_e32 v217, v217, v203
	v_sub_f32_e32 v218, v218, v203
	v_sub_f32_e32 v219, v219, v203
	v_sub_f32_e32 v220, v220, v203
	v_sub_f32_e32 v221, v221, v203

.LBB0_443:
	v_add3_u32 v198, s20, v180, v182
	ds_read_b128 v[82:85], v198 offset:12800
	ds_read_b128 v[186:189], v198 offset:12832
	s_mul_i32 s12, s19, 0x4800
	v_add_u32_e32 v223, s12, v185
	v_max_f32_e32 v204, v2, v3
	s_waitcnt lgkmcnt(1)
	v_mfma_f32_32x32x16_bf16 v[82:97], v[82:85], v[98:101], v[206:221]
	v_max3_f32 v204, v204, v4, v5
	v_max3_f32 v204, v204, v6, v7
	v_max3_f32 v204, v204, v8, v9
	v_max3_f32 v204, v204, v10, v11
	v_max3_f32 v204, v204, v12, v13
	v_max3_f32 v204, v204, v14, v15
	v_max3_f32 v204, v204, v16, v17
	s_waitcnt lgkmcnt(0)
	v_mfma_f32_32x32x16_bf16 v[82:97], v[186:189], v[102:105], v[82:97]
	ds_read_b128 v[186:189], v198 offset:12864
	ds_read_b128 v[190:193], v198 offset:12896
	v_exp_f32_e32 v2, v2
	v_exp_f32_e32 v3, v3
	v_exp_f32_e32 v4, v4
	v_exp_f32_e32 v5, v5
	v_exp_f32_e32 v6, v6
	v_exp_f32_e32 v7, v7
	s_waitcnt lgkmcnt(1)
	v_mfma_f32_32x32x16_bf16 v[82:97], v[186:189], v[106:109], v[82:97]
	v_exp_f32_e32 v8, v8
	v_exp_f32_e32 v9, v9
	v_add_f32_e32 v202, v3, v2
	v_add_f32_e32 v202, v4, v202
	v_add_f32_e32 v202, v5, v202
	v_add_f32_e32 v202, v6, v202
	v_add_f32_e32 v202, v7, v202
	s_waitcnt lgkmcnt(0)
	v_mfma_f32_32x32x16_bf16 v[82:97], v[190:193], v[110:113], v[82:97]
	ds_read_b128 v[186:189], v198 offset:12928
	ds_read_b128 v[190:193], v198 offset:12960
	v_exp_f32_e32 v10, v10
	v_exp_f32_e32 v11, v11
	v_exp_f32_e32 v12, v12
	v_exp_f32_e32 v13, v13
	v_add_f32_e32 v202, v8, v202
	v_add_f32_e32 v202, v9, v202
	s_waitcnt lgkmcnt(1)
	v_mfma_f32_32x32x16_bf16 v[82:97], v[186:189], v[114:117], v[82:97]
	ds_read_b128 v[186:189], v198 offset:12992
	v_exp_f32_e32 v14, v14
	v_exp_f32_e32 v15, v15
	v_exp_f32_e32 v16, v16
	v_add_f32_e32 v202, v10, v202
	s_waitcnt lgkmcnt(1)
	v_mfma_f32_32x32x16_bf16 v[82:97], v[190:193], v[118:121], v[82:97]
	ds_read_b128 v[190:193], v198 offset:13024
	v_add_f32_e32 v202, v11, v202
	v_add_f32_e32 v202, v12, v202
	v_add_f32_e32 v202, v13, v202
	v_add_f32_e32 v202, v14, v202
	v_add_f32_e32 v202, v15, v202
	v_add_f32_e32 v202, v16, v202
	s_waitcnt lgkmcnt(1)
	v_mfma_f32_32x32x16_bf16 v[82:97], v[186:189], v[122:125], v[82:97]
	ds_read_b128 v[186:189], v198 offset:13056
	ds_bpermute_b32 v205, v178, v204
	v_exp_f32_e32 v17, v17
	s_waitcnt lgkmcnt(2)
	v_mfma_f32_32x32x16_bf16 v[82:97], v[190:193], v[126:129], v[82:97]
	ds_read_b128 v[190:193], v198 offset:13088
	ds_read_b128 v[194:197], v198 offset:13120
	ds_read_b128 v[198:201], v198 offset:13152
	s_waitcnt lgkmcnt(4)
	v_mfma_f32_32x32x16_bf16 v[82:97], v[186:189], v[130:133], v[82:97]
	ds_read_b128 v[186:189], v223 offset:51200
	s_waitcnt lgkmcnt(3)
	v_mfma_f32_32x32x16_bf16 v[82:97], v[190:193], v[134:137], v[82:97]
	ds_read_b128 v[190:193], v223 offset:51232
	s_waitcnt lgkmcnt(3)
	v_mfma_f32_32x32x16_bf16 v[82:97], v[194:197], v[138:141], v[82:97]
	v_cvt_pk_bf16_f32 v194, v2, v3
	v_cvt_pk_bf16_f32 v195, v4, v5
	v_cvt_pk_bf16_f32 v196, v6, v7
	v_cvt_pk_bf16_f32 v197, v8, v9
	s_waitcnt lgkmcnt(1)
	s_nop 0
	v_mfma_f32_32x32x16_bf16 v[18:33], v[186:189], v[194:197], v[18:33]
	v_add_f32_e32 v202, v17, v202
	v_add_f32_e32 v183, v183, v202
	v_cvt_pk_bf16_f32 v186, v10, v11
	v_cvt_pk_bf16_f32 v187, v12, v13
	v_cvt_pk_bf16_f32 v188, v14, v15
	v_cvt_pk_bf16_f32 v189, v16, v17
	s_waitcnt lgkmcnt(0)
	v_max_f32_e32 v222, v204, v205
	v_mfma_f32_32x32x16_bf16 v[18:33], v[190:193], v[186:189], v[18:33]
	ds_read_b128 v[190:193], v223 offset:55808
	ds_read_b128 v[202:205], v223 offset:55840
	ds_read_b128 v[2:5], v223 offset:60448
	ds_read_b128 v[6:9], v223 offset:65024
	s_waitcnt lgkmcnt(3)
	v_mfma_f32_32x32x16_bf16 v[34:49], v[190:193], v[194:197], v[34:49]
	ds_read_b128 v[190:193], v223 offset:60416
	s_waitcnt lgkmcnt(0)
	v_mfma_f32_32x32x16_bf16 v[50:65], v[190:193], v[194:197], v[50:65]
	v_mfma_f32_32x32x16_bf16 v[50:65], v[2:5], v[186:189], v[50:65]
	ds_read_b128 v[2:5], v223 offset:65056
	v_mfma_f32_32x32x16_bf16 v[66:81], v[6:9], v[194:197], v[66:81]
	s_waitcnt lgkmcnt(0)
	v_mfma_f32_32x32x16_bf16 v[66:81], v[2:5], v[186:189], v[66:81]
	v_mfma_f32_32x32x16_bf16 v[34:49], v[202:205], v[186:189], v[34:49]
	v_cmp_lt_f32_e32 vcc, s2, v222
	v_mfma_f32_32x32x16_bf16 v[2:17], v[198:201], v[142:145], v[82:97]
	s_cbranch_vccz .LBB0_445
	v_max_f32_e32 v202, v222, v222
	v_max_f32_e32 v203, 0, v202
	v_exp_f32_e64 v202, -v203
	v_add_f32_e32 v184, v184, v203
	v_mul_f32_e32 v183, v183, v202
	v_pk_mul_f32 v[32:33], v[32:33], v[202:203] op_sel_hi:[1,0]
	v_pk_mul_f32 v[30:31], v[30:31], v[202:203] op_sel_hi:[1,0]
	v_pk_mul_f32 v[28:29], v[28:29], v[202:203] op_sel_hi:[1,0]
	v_pk_mul_f32 v[26:27], v[26:27], v[202:203] op_sel_hi:[1,0]
	v_pk_mul_f32 v[24:25], v[24:25], v[202:203] op_sel_hi:[1,0]
	v_pk_mul_f32 v[22:23], v[22:23], v[202:203] op_sel_hi:[1,0]
	v_pk_mul_f32 v[20:21], v[20:21], v[202:203] op_sel_hi:[1,0]
	v_pk_mul_f32 v[18:19], v[18:19], v[202:203] op_sel_hi:[1,0]
	v_pk_mul_f32 v[48:49], v[202:203], v[48:49] op_sel_hi:[0,1]
	v_pk_mul_f32 v[46:47], v[202:203], v[46:47] op_sel_hi:[0,1]
	v_pk_mul_f32 v[44:45], v[202:203], v[44:45] op_sel_hi:[0,1]
	v_pk_mul_f32 v[42:43], v[202:203], v[42:43] op_sel_hi:[0,1]
	v_pk_mul_f32 v[40:41], v[202:203], v[40:41] op_sel_hi:[0,1]
	v_pk_mul_f32 v[38:39], v[202:203], v[38:39] op_sel_hi:[0,1]
	v_pk_mul_f32 v[36:37], v[202:203], v[36:37] op_sel_hi:[0,1]
	v_pk_mul_f32 v[34:35], v[202:203], v[34:35] op_sel_hi:[0,1]
	v_pk_mul_f32 v[64:65], v[202:203], v[64:65] op_sel_hi:[0,1]
	v_pk_mul_f32 v[62:63], v[202:203], v[62:63] op_sel_hi:[0,1]
	v_pk_mul_f32 v[60:61], v[202:203], v[60:61] op_sel_hi:[0,1]
	v_pk_mul_f32 v[58:59], v[202:203], v[58:59] op_sel_hi:[0,1]
	v_pk_mul_f32 v[56:57], v[202:203], v[56:57] op_sel_hi:[0,1]
	v_pk_mul_f32 v[54:55], v[202:203], v[54:55] op_sel_hi:[0,1]
	v_pk_mul_f32 v[52:53], v[202:203], v[52:53] op_sel_hi:[0,1]
	v_pk_mul_f32 v[50:51], v[202:203], v[50:51] op_sel_hi:[0,1]
	v_pk_mul_f32 v[80:81], v[202:203], v[80:81] op_sel_hi:[0,1]
	v_pk_mul_f32 v[78:79], v[202:203], v[78:79] op_sel_hi:[0,1]
	v_pk_mul_f32 v[76:77], v[202:203], v[76:77] op_sel_hi:[0,1]
	v_pk_mul_f32 v[74:75], v[202:203], v[74:75] op_sel_hi:[0,1]
	v_pk_mul_f32 v[72:73], v[202:203], v[72:73] op_sel_hi:[0,1]
	v_pk_mul_f32 v[70:71], v[202:203], v[70:71] op_sel_hi:[0,1]
	v_pk_mul_f32 v[68:69], v[202:203], v[68:69] op_sel_hi:[0,1]
	v_pk_mul_f32 v[66:67], v[202:203], v[66:67] op_sel_hi:[0,1]
	v_sub_f32_e32 v2, v2, v203
	v_sub_f32_e32 v3, v3, v203
	v_sub_f32_e32 v4, v4, v203
	v_sub_f32_e32 v5, v5, v203
	v_sub_f32_e32 v6, v6, v203
	v_sub_f32_e32 v7, v7, v203
	v_sub_f32_e32 v8, v8, v203
	v_sub_f32_e32 v9, v9, v203
	v_sub_f32_e32 v10, v10, v203
	v_sub_f32_e32 v11, v11, v203
	v_sub_f32_e32 v12, v12, v203
	v_sub_f32_e32 v13, v13, v203
	v_sub_f32_e32 v14, v14, v203
	v_sub_f32_e32 v15, v15, v203
	v_sub_f32_e32 v16, v16, v203
	v_sub_f32_e32 v17, v17, v203
	v_sub_f32_e32 v206, v206, v203
	v_sub_f32_e32 v207, v207, v203
	v_sub_f32_e32 v208, v208, v203
	v_sub_f32_e32 v209, v209, v203
	v_sub_f32_e32 v210, v210, v203
	v_sub_f32_e32 v211, v211, v203
	v_sub_f32_e32 v212, v212, v203
	v_sub_f32_e32 v213, v213, v203
	v_sub_f32_e32 v214, v214, v203
	v_sub_f32_e32 v215, v215, v203
	v_sub_f32_e32 v216, v216, v203
	v_sub_f32_e32 v217, v217, v203
	v_sub_f32_e32 v218, v218, v203
	v_sub_f32_e32 v219, v219, v203
	v_sub_f32_e32 v220, v220, v203
	v_sub_f32_e32 v221, v221, v203
